# GEMM loop: redundant mid-segment s_setprio 0/1 pair removed (priority held across the 32 MFMAs)
# baseline (speedup 1.0000x reference)
; #define LAS __attribute__((address_space(3)))
; __global__ void __launch_bounds__(NWAVES * 64, 2) fwd_megakernel(Args args) {
;     ...
;     bf16_t* W1 = (bf16_t*)(ws + WS_W1); bf16_t* WD1 = (bf16_t*)(ws + WS_WD1); bf16_t* VT = (bf16_t*)(ws + WS_VT);
;     bf16_t* WQK = (bf16_t*)(ws + WS_WQK); bf16_t* WV = (bf16_t*)(ws + WS_WV); bf16_t* WO = (bf16_t*)(ws + WS_WO);
;     bf16_t* W2 = (bf16_t*)(ws + WS_W2); bf16_t* WD2 = (bf16_t*)(ws + WS_WD2); bf16_t* WPG = (bf16_t*)(ws + WS_WPG); bf16_t* WPP = (bf16_t*)(ws + WS_WPP);
;     bf16_t* PB = (bf16_t*)(ws + WS_PB); bf16_t* XB = (bf16_t*)(ws + WS_XB); bf16_t* HB = (bf16_t*)(ws + WS_H); bf16_t* QKB = (bf16_t*)(ws + WS_QK); bf16_t* CAT = (bf16_t*)(ws + WS_CAT);
;     {
;         LAS float* scr = (LAS float*)(lds + wave * 16640);
;         constexpr int I_GU = (DM / 64) * (FF / 64), I_DN = (FF / 64) * (DM / 64), I_IN = (DM / 64) * (1024 / 64), I_SQ = (DM / 64) * (DM / 64), I_PP = (PLE / 64) * (DM / 64);
;         constexpr int NITEMS = 4 * I_GU + 2 * I_DN + 6 * I_IN + 2 * I_SQ + I_PP;
;         for (int it = gw; it < NITEMS; it += NGW) {
.LBB0_28:
	v_writelane_b32 v250, s30, 30
	s_nop 1
	v_writelane_b32 v250, s31, 31
	v_writelane_b32 v250, s27, 32
	s_or_b64 exec, exec, s[4:5]
	s_lshr_b32 s64, s3, 6
	s_lshl_b32 s1, s26, 3
	s_add_i32 s1, s1, s64
	s_add_u32 s4, s60, 0x200000
	s_addc_u32 s5, s61, 0
	v_writelane_b32 v250, s4, 34
	v_and_b32_e32 v168, 63, v166
	s_nop 0
	v_writelane_b32 v250, s5, 35
	s_add_u32 s4, s60, 0x2e00000
	s_addc_u32 s5, s61, 0
	v_writelane_b32 v250, s4, 36
	s_nop 1
	v_writelane_b32 v250, s5, 37
	s_add_u32 s4, s60, 0x4400000
	s_addc_u32 s5, s61, 0
	v_writelane_b32 v250, s4, 38
	s_nop 1
	v_writelane_b32 v250, s5, 39
	s_add_u32 s4, s60, 0x5400000
	s_addc_u32 s5, s61, 0
	v_writelane_b32 v250, s4, 40
	s_nop 1
	v_writelane_b32 v250, s5, 41
	s_add_u32 s4, s60, 0x5c00000
	s_addc_u32 s5, s61, 0
	v_writelane_b32 v250, s4, 42
	s_nop 1
	v_writelane_b32 v250, s5, 43
	s_add_u32 s4, s60, 0x6400000
	s_addc_u32 s5, s61, 0
	v_writelane_b32 v250, s4, 44
	s_nop 1
	v_writelane_b32 v250, s5, 45
	s_add_u32 s4, s60, 0x9000000
	s_addc_u32 s5, s61, 0
	v_writelane_b32 v250, s4, 46
	s_nop 1
	v_writelane_b32 v250, s5, 47
	s_add_u32 s4, s60, 0xa600000
	s_addc_u32 s5, s61, 0
	v_writelane_b32 v250, s4, 48
	s_nop 1
	v_writelane_b32 v250, s5, 49
	s_add_u32 s4, s60, 0xae00000
	s_addc_u32 s5, s61, 0
	v_writelane_b32 v250, s4, 50
	s_cmpk_gt_i32 s1, 0x567f
	s_nop 0
	v_writelane_b32 v250, s5, 51
	v_writelane_b32 v250, s1, 52
	s_cbranch_scc1 .LBB0_120
	v_lshlrev_b32_e32 v66, 2, v168
	v_and_b32_e32 v0, 7, v168
	v_lshlrev_b32_e32 v67, 5, v0
	v_lshrrev_b32_e32 v79, 3, v168
	s_mul_i32 s3, s64, 0x4100
	v_mul_u32_u24_e32 v77, 0x820, v0
	v_lshl_add_u32 v77, v79, 2, v77
	v_add_u32_e32 v77, s3, v77
	v_lshlrev_b32_e32 v92, 4, v0
	v_lshrrev_b32_e32 v93, 4, v168
	v_and_b32_e32 v94, 15, v168
	v_lshlrev_b32_e32 v94, 4, v94
	v_mul_u32_u24_e32 v95, 0x104, v93
	v_add3_u32 v76, v95, v94, s3
	v_readlane_b32 s55, v250, 52
	s_lshl_b32 s1, s62, 3
	s_mov_b32 s59, 0

; __device__ __forceinline__ void p0_item(const float* W, int ldw, int col0, int k0, const float* gain, bf16_t* WT, int K, int drow0, LAS float* scr, int lane) {
;     ...
;     const float* src = W + (size_t)k0 * ldw + col0 + lane;
; #pragma unroll
;     for (int i = 0; i < 64; ++i) v[i] = src[(size_t)i * ldw];
.Lp0_rows:
	s_mul_i32 s4, s33, s30
	s_add_u32 s4, s4, s31
	s_lshl_b32 s4, s4, 2
	s_add_u32 s40, s28, s4
	s_addc_u32 s41, s29, 0
	s_lshl_b32 s5, s30, 2
	v_mul_lo_u32 v66, v93, s5
	v_add_u32_e32 v66, v66, v94
	s_lshl_b32 s5, s5, 2
	global_load_dwordx4 v[2:5], v66, s[40:41]
	s_add_u32 s40, s40, s5
	s_addc_u32 s41, s41, 0
	global_load_dwordx4 v[6:9], v66, s[40:41]
	s_add_u32 s40, s40, s5
	s_addc_u32 s41, s41, 0
	global_load_dwordx4 v[10:13], v66, s[40:41]
	s_add_u32 s40, s40, s5
	s_addc_u32 s41, s41, 0
	global_load_dwordx4 v[14:17], v66, s[40:41]
	s_add_u32 s40, s40, s5
	s_addc_u32 s41, s41, 0
	global_load_dwordx4 v[18:21], v66, s[40:41]
	s_add_u32 s40, s40, s5
	s_addc_u32 s41, s41, 0
	global_load_dwordx4 v[22:25], v66, s[40:41]
	s_add_u32 s40, s40, s5
	s_addc_u32 s41, s41, 0
	global_load_dwordx4 v[26:29], v66, s[40:41]
	s_add_u32 s40, s40, s5
	s_addc_u32 s41, s41, 0
	global_load_dwordx4 v[30:33], v66, s[40:41]
	s_add_u32 s40, s40, s5
	s_addc_u32 s41, s41, 0
	global_load_dwordx4 v[34:37], v66, s[40:41]
	s_add_u32 s40, s40, s5
	s_addc_u32 s41, s41, 0
	global_load_dwordx4 v[38:41], v66, s[40:41]
	s_add_u32 s40, s40, s5
	s_addc_u32 s41, s41, 0
	global_load_dwordx4 v[42:45], v66, s[40:41]
	s_add_u32 s40, s40, s5
	s_addc_u32 s41, s41, 0
	global_load_dwordx4 v[46:49], v66, s[40:41]
	s_add_u32 s40, s40, s5
	s_addc_u32 s41, s41, 0
	global_load_dwordx4 v[50:53], v66, s[40:41]
	s_add_u32 s40, s40, s5
	s_addc_u32 s41, s41, 0
	global_load_dwordx4 v[54:57], v66, s[40:41]
	s_add_u32 s40, s40, s5
	s_addc_u32 s41, s41, 0
	global_load_dwordx4 v[58:61], v66, s[40:41]
	s_add_u32 s40, s40, s5
	s_addc_u32 s41, s41, 0
	global_load_dwordx4 v[62:65], v66, s[40:41]
	s_cmp_eq_u32 s59, 0
	s_cbranch_scc1 .Lp0_first
; #define LAS __attribute__((address_space(3)))
; __device__ __forceinline__ unsigned cvtpk(float lo, float hi) { f32x2 v = {lo, hi}; bf16x2_t b = __builtin_convertvector(v, bf16x2_t); return __builtin_bit_cast(unsigned, b); }
; __device__ __forceinline__ void p0_item(const float* W, int ldw, int col0, int k0, const float* gain, bf16_t* WT, int K, int drow0, LAS float* scr, int lane) {
;     ...
;     for (int j = 0; j < 8; ++j) { const int n = (lane >> 3) + 8 * j; const LAS float* s = scr + (8 * c) * 65 + n;
;         u32x4 o; o.x = cvtpk(s[0 * 65] * g0[0], s[1 * 65] * g0[1]); o.y = cvtpk(s[2 * 65] * g0[2], s[3 * 65] * g0[3]); o.z = cvtpk(s[4 * 65] * g1[0], s[5 * 65] * g1[1]); o.w = cvtpk(s[6 * 65] * g1[2], s[7 * 65] * g1[3]);
;         *(u32x4*)(WT + (size_t)(drow0 + n) * K + k0 + 8 * c) = o; }
	ds_read_b32 v80, v77 offset:0
	ds_read_b32 v81, v77 offset:260
	ds_read_b32 v82, v77 offset:520
	ds_read_b32 v83, v77 offset:780
	ds_read_b32 v84, v77 offset:1040
	ds_read_b32 v85, v77 offset:1300
	ds_read_b32 v86, v77 offset:1560
	ds_read_b32 v87, v77 offset:1820
	s_waitcnt lgkmcnt(0)
	v_pk_mul_f32 v[84:85], v[84:85], v[100:101]
	v_pk_mul_f32 v[86:87], v[86:87], v[102:103]
	v_pk_mul_f32 v[80:81], v[80:81], v[96:97]
	v_pk_mul_f32 v[82:83], v[82:83], v[98:99]
	v_cvt_pk_bf16_f32 v90, v84, v85
	v_cvt_pk_bf16_f32 v91, v86, v87
	v_cvt_pk_bf16_f32 v88, v80, v81
	v_cvt_pk_bf16_f32 v89, v82, v83
	ds_read_b32 v80, v77 offset:32
	ds_read_b32 v81, v77 offset:292
	ds_read_b32 v82, v77 offset:552
	ds_read_b32 v83, v77 offset:812
	ds_read_b32 v84, v77 offset:1072
	ds_read_b32 v85, v77 offset:1332
	ds_read_b32 v86, v77 offset:1592
	ds_read_b32 v87, v77 offset:1852
	global_store_dwordx4 v104, v[88:91], s[48:49]
	s_add_u32 s48, s48, s50
	s_addc_u32 s49, s49, 0
	s_waitcnt lgkmcnt(0)
	v_pk_mul_f32 v[84:85], v[84:85], v[100:101]
	v_pk_mul_f32 v[86:87], v[86:87], v[102:103]
	v_pk_mul_f32 v[80:81], v[80:81], v[96:97]
	v_pk_mul_f32 v[82:83], v[82:83], v[98:99]
	v_cvt_pk_bf16_f32 v90, v84, v85
	v_cvt_pk_bf16_f32 v91, v86, v87
	v_cvt_pk_bf16_f32 v88, v80, v81
	v_cvt_pk_bf16_f32 v89, v82, v83
	ds_read_b32 v80, v77 offset:64
	ds_read_b32 v81, v77 offset:324
	ds_read_b32 v82, v77 offset:584
	ds_read_b32 v83, v77 offset:844
	ds_read_b32 v84, v77 offset:1104
	ds_read_b32 v85, v77 offset:1364
	ds_read_b32 v86, v77 offset:1624
	ds_read_b32 v87, v77 offset:1884
	global_store_dwordx4 v104, v[88:91], s[48:49]
	s_add_u32 s48, s48, s50
	s_addc_u32 s49, s49, 0
	s_waitcnt lgkmcnt(0)
	v_pk_mul_f32 v[84:85], v[84:85], v[100:101]
	v_pk_mul_f32 v[86:87], v[86:87], v[102:103]
	v_pk_mul_f32 v[80:81], v[80:81], v[96:97]
	v_pk_mul_f32 v[82:83], v[82:83], v[98:99]
	v_cvt_pk_bf16_f32 v90, v84, v85
	v_cvt_pk_bf16_f32 v91, v86, v87
	v_cvt_pk_bf16_f32 v88, v80, v81
	v_cvt_pk_bf16_f32 v89, v82, v83
	ds_read_b32 v80, v77 offset:96
	ds_read_b32 v81, v77 offset:356
	ds_read_b32 v82, v77 offset:616
	ds_read_b32 v83, v77 offset:876
	ds_read_b32 v84, v77 offset:1136
	ds_read_b32 v85, v77 offset:1396
	ds_read_b32 v86, v77 offset:1656
	ds_read_b32 v87, v77 offset:1916
	global_store_dwordx4 v104, v[88:91], s[48:49]
	s_add_u32 s48, s48, s50
	s_addc_u32 s49, s49, 0
	s_waitcnt lgkmcnt(0)
	v_pk_mul_f32 v[84:85], v[84:85], v[100:101]
	v_pk_mul_f32 v[86:87], v[86:87], v[102:103]
	v_pk_mul_f32 v[80:81], v[80:81], v[96:97]
	v_pk_mul_f32 v[82:83], v[82:83], v[98:99]
	v_cvt_pk_bf16_f32 v90, v84, v85
	v_cvt_pk_bf16_f32 v91, v86, v87
	v_cvt_pk_bf16_f32 v88, v80, v81
	v_cvt_pk_bf16_f32 v89, v82, v83
	ds_read_b32 v80, v77 offset:128
	ds_read_b32 v81, v77 offset:388
	ds_read_b32 v82, v77 offset:648
	ds_read_b32 v83, v77 offset:908
	ds_read_b32 v84, v77 offset:1168
	ds_read_b32 v85, v77 offset:1428
	ds_read_b32 v86, v77 offset:1688
	ds_read_b32 v87, v77 offset:1948
	global_store_dwordx4 v104, v[88:91], s[48:49]
	s_add_u32 s48, s48, s50
	s_addc_u32 s49, s49, 0
	s_waitcnt lgkmcnt(0)
	v_pk_mul_f32 v[84:85], v[84:85], v[100:101]
	v_pk_mul_f32 v[86:87], v[86:87], v[102:103]
	v_pk_mul_f32 v[80:81], v[80:81], v[96:97]
	v_pk_mul_f32 v[82:83], v[82:83], v[98:99]
	v_cvt_pk_bf16_f32 v90, v84, v85
	v_cvt_pk_bf16_f32 v91, v86, v87
	v_cvt_pk_bf16_f32 v88, v80, v81
	v_cvt_pk_bf16_f32 v89, v82, v83
	ds_read_b32 v80, v77 offset:160
	ds_read_b32 v81, v77 offset:420
	ds_read_b32 v82, v77 offset:680
	ds_read_b32 v83, v77 offset:940
	ds_read_b32 v84, v77 offset:1200
	ds_read_b32 v85, v77 offset:1460
	ds_read_b32 v86, v77 offset:1720
	ds_read_b32 v87, v77 offset:1980
	global_store_dwordx4 v104, v[88:91], s[48:49]
	s_add_u32 s48, s48, s50
	s_addc_u32 s49, s49, 0
	s_waitcnt lgkmcnt(0)
	v_pk_mul_f32 v[84:85], v[84:85], v[100:101]
	v_pk_mul_f32 v[86:87], v[86:87], v[102:103]
	v_pk_mul_f32 v[80:81], v[80:81], v[96:97]
	v_pk_mul_f32 v[82:83], v[82:83], v[98:99]
	v_cvt_pk_bf16_f32 v90, v84, v85
	v_cvt_pk_bf16_f32 v91, v86, v87
	v_cvt_pk_bf16_f32 v88, v80, v81
	v_cvt_pk_bf16_f32 v89, v82, v83
	ds_read_b32 v80, v77 offset:192
	ds_read_b32 v81, v77 offset:452
	ds_read_b32 v82, v77 offset:712
	ds_read_b32 v83, v77 offset:972
	ds_read_b32 v84, v77 offset:1232
	ds_read_b32 v85, v77 offset:1492
	ds_read_b32 v86, v77 offset:1752
	ds_read_b32 v87, v77 offset:2012
	global_store_dwordx4 v104, v[88:91], s[48:49]
	s_add_u32 s48, s48, s50
	s_addc_u32 s49, s49, 0
	s_waitcnt lgkmcnt(0)
	v_pk_mul_f32 v[84:85], v[84:85], v[100:101]
	v_pk_mul_f32 v[86:87], v[86:87], v[102:103]
	v_pk_mul_f32 v[80:81], v[80:81], v[96:97]
	v_pk_mul_f32 v[82:83], v[82:83], v[98:99]
	v_cvt_pk_bf16_f32 v90, v84, v85
	v_cvt_pk_bf16_f32 v91, v86, v87
	v_cvt_pk_bf16_f32 v88, v80, v81
	v_cvt_pk_bf16_f32 v89, v82, v83
	ds_read_b32 v80, v77 offset:224
	ds_read_b32 v81, v77 offset:484
	ds_read_b32 v82, v77 offset:744
	ds_read_b32 v83, v77 offset:1004
	ds_read_b32 v84, v77 offset:1264
	ds_read_b32 v85, v77 offset:1524
	ds_read_b32 v86, v77 offset:1784
	ds_read_b32 v87, v77 offset:2044
	global_store_dwordx4 v104, v[88:91], s[48:49]
	s_add_u32 s48, s48, s50
	s_addc_u32 s49, s49, 0
	s_waitcnt lgkmcnt(0)
	v_pk_mul_f32 v[84:85], v[84:85], v[100:101]
	v_pk_mul_f32 v[86:87], v[86:87], v[102:103]
	v_pk_mul_f32 v[80:81], v[80:81], v[96:97]
	v_pk_mul_f32 v[82:83], v[82:83], v[98:99]
	v_cvt_pk_bf16_f32 v90, v84, v85
	v_cvt_pk_bf16_f32 v91, v86, v87
	v_cvt_pk_bf16_f32 v88, v80, v81
	v_cvt_pk_bf16_f32 v89, v82, v83
	global_store_dwordx4 v104, v[88:91], s[48:49]
	s_branch .Lp0_fill

; #define LAS __attribute__((address_space(3)))
; __device__ __forceinline__ void p0_item(const float* W, int ldw, int col0, int k0, const float* gain, bf16_t* WT, int K, int drow0, LAS float* scr, int lane) {
;     float v[64];
;     const float* src = W + (size_t)k0 * ldw + col0 + lane;
; #pragma unroll
;     for (int i = 0; i < 64; ++i) v[i] = src[(size_t)i * ldw];
;     const int c = lane & 7;
;     f32x4 g0 = {1.f, 1.f, 1.f, 1.f}, g1 = {1.f, 1.f, 1.f, 1.f};
;     if (gain) { g0 = *(const f32x4*)(gain + k0 + 8 * c); g1 = *(const f32x4*)(gain + k0 + 8 * c + 4); }
; #pragma unroll
;     for (int i = 0; i < 64; ++i) scr[i * 65 + lane] = v[i];
;     asm volatile("s_waitcnt lgkmcnt(0)" ::: "memory");
.Lp0_fill:
	s_waitcnt vmcnt(23)
	ds_write_b32 v76, v2 offset:0
	ds_write_b32 v76, v3 offset:4
	ds_write_b32 v76, v4 offset:8
	ds_write_b32 v76, v5 offset:12
	s_waitcnt vmcnt(22)
	ds_write_b32 v76, v6 offset:1040
	ds_write_b32 v76, v7 offset:1044
	ds_write_b32 v76, v8 offset:1048
	ds_write_b32 v76, v9 offset:1052
	s_waitcnt vmcnt(21)
	ds_write_b32 v76, v10 offset:2080
	ds_write_b32 v76, v11 offset:2084
	ds_write_b32 v76, v12 offset:2088
	ds_write_b32 v76, v13 offset:2092
	s_waitcnt vmcnt(20)
	ds_write_b32 v76, v14 offset:3120
	ds_write_b32 v76, v15 offset:3124
	ds_write_b32 v76, v16 offset:3128
	ds_write_b32 v76, v17 offset:3132
	s_waitcnt vmcnt(19)
	ds_write_b32 v76, v18 offset:4160
	ds_write_b32 v76, v19 offset:4164
	ds_write_b32 v76, v20 offset:4168
	ds_write_b32 v76, v21 offset:4172
	s_waitcnt vmcnt(18)
	ds_write_b32 v76, v22 offset:5200
	ds_write_b32 v76, v23 offset:5204
	ds_write_b32 v76, v24 offset:5208
	ds_write_b32 v76, v25 offset:5212
	s_waitcnt vmcnt(17)
	ds_write_b32 v76, v26 offset:6240
	ds_write_b32 v76, v27 offset:6244
	ds_write_b32 v76, v28 offset:6248
	ds_write_b32 v76, v29 offset:6252
	s_waitcnt vmcnt(16)
	ds_write_b32 v76, v30 offset:7280
	ds_write_b32 v76, v31 offset:7284
	ds_write_b32 v76, v32 offset:7288
	ds_write_b32 v76, v33 offset:7292
	s_waitcnt vmcnt(15)
	ds_write_b32 v76, v34 offset:8320
	ds_write_b32 v76, v35 offset:8324
	ds_write_b32 v76, v36 offset:8328
	ds_write_b32 v76, v37 offset:8332
	s_waitcnt vmcnt(14)
	ds_write_b32 v76, v38 offset:9360
	ds_write_b32 v76, v39 offset:9364
	ds_write_b32 v76, v40 offset:9368
	ds_write_b32 v76, v41 offset:9372
	s_waitcnt vmcnt(13)
	ds_write_b32 v76, v42 offset:10400
	ds_write_b32 v76, v43 offset:10404
	ds_write_b32 v76, v44 offset:10408
	ds_write_b32 v76, v45 offset:10412
	s_waitcnt vmcnt(12)
	ds_write_b32 v76, v46 offset:11440
	ds_write_b32 v76, v47 offset:11444
	ds_write_b32 v76, v48 offset:11448
	ds_write_b32 v76, v49 offset:11452
	s_waitcnt vmcnt(11)
	ds_write_b32 v76, v50 offset:12480
	ds_write_b32 v76, v51 offset:12484
	ds_write_b32 v76, v52 offset:12488
	ds_write_b32 v76, v53 offset:12492
	s_waitcnt vmcnt(10)
	ds_write_b32 v76, v54 offset:13520
	ds_write_b32 v76, v55 offset:13524
	ds_write_b32 v76, v56 offset:13528
	ds_write_b32 v76, v57 offset:13532
	s_waitcnt vmcnt(9)
	ds_write_b32 v76, v58 offset:14560
	ds_write_b32 v76, v59 offset:14564
	ds_write_b32 v76, v60 offset:14568
	ds_write_b32 v76, v61 offset:14572
	s_waitcnt vmcnt(8)
	ds_write_b32 v76, v62 offset:15600
	ds_write_b32 v76, v63 offset:15604
	ds_write_b32 v76, v64 offset:15608
	ds_write_b32 v76, v65 offset:15612
	v_mov_b32_e32 v96, v68
	v_mov_b32_e32 v97, v69
	v_mov_b32_e32 v98, v70
	v_mov_b32_e32 v99, v71
	v_mov_b32_e32 v100, v72
	v_mov_b32_e32 v101, v73
	v_mov_b32_e32 v102, v74
	v_mov_b32_e32 v103, v75
	s_mul_i32 s4, s39, s38
	s_add_u32 s4, s4, s33
	s_lshl_b32 s4, s4, 1
	s_add_u32 s48, s36, s4
	s_addc_u32 s49, s37, 0
	s_lshl_b32 s6, s38, 1
	v_mul_lo_u32 v104, v79, s6
	v_add_u32_e32 v104, v104, v92
	s_lshl_b32 s50, s38, 4
	s_mov_b32 s59, 1
	s_waitcnt lgkmcnt(0)
	s_add_i32 s55, s55, s1
	s_cmpk_gt_i32 s55, 0x567f
	s_cbranch_scc0 .Lp0_loop
; #define LAS __attribute__((address_space(3)))
; __device__ __forceinline__ unsigned cvtpk(float lo, float hi) { f32x2 v = {lo, hi}; bf16x2_t b = __builtin_convertvector(v, bf16x2_t); return __builtin_bit_cast(unsigned, b); }
; __device__ __forceinline__ void p0_item(const float* W, int ldw, int col0, int k0, const float* gain, bf16_t* WT, int K, int drow0, LAS float* scr, int lane) {
;     ...
;     for (int j = 0; j < 8; ++j) { const int n = (lane >> 3) + 8 * j; const LAS float* s = scr + (8 * c) * 65 + n;
;         u32x4 o; o.x = cvtpk(s[0 * 65] * g0[0], s[1 * 65] * g0[1]); o.y = cvtpk(s[2 * 65] * g0[2], s[3 * 65] * g0[3]); o.z = cvtpk(s[4 * 65] * g1[0], s[5 * 65] * g1[1]); o.w = cvtpk(s[6 * 65] * g1[2], s[7 * 65] * g1[3]);
;         *(u32x4*)(WT + (size_t)(drow0 + n) * K + k0 + 8 * c) = o; }
;     asm volatile("s_waitcnt lgkmcnt(0)" ::: "memory");
	ds_read_b32 v80, v77 offset:0
	ds_read_b32 v81, v77 offset:260
	ds_read_b32 v82, v77 offset:520
	ds_read_b32 v83, v77 offset:780
	ds_read_b32 v84, v77 offset:1040
	ds_read_b32 v85, v77 offset:1300
	ds_read_b32 v86, v77 offset:1560
	ds_read_b32 v87, v77 offset:1820
	s_waitcnt lgkmcnt(0)
	v_pk_mul_f32 v[84:85], v[84:85], v[100:101]
	v_pk_mul_f32 v[86:87], v[86:87], v[102:103]
	v_pk_mul_f32 v[80:81], v[80:81], v[96:97]
	v_pk_mul_f32 v[82:83], v[82:83], v[98:99]
	v_cvt_pk_bf16_f32 v90, v84, v85
	v_cvt_pk_bf16_f32 v91, v86, v87
	v_cvt_pk_bf16_f32 v88, v80, v81
	v_cvt_pk_bf16_f32 v89, v82, v83
	ds_read_b32 v80, v77 offset:32
	ds_read_b32 v81, v77 offset:292
	ds_read_b32 v82, v77 offset:552
	ds_read_b32 v83, v77 offset:812
	ds_read_b32 v84, v77 offset:1072
	ds_read_b32 v85, v77 offset:1332
	ds_read_b32 v86, v77 offset:1592
	ds_read_b32 v87, v77 offset:1852
	global_store_dwordx4 v104, v[88:91], s[48:49]
	s_add_u32 s48, s48, s50
	s_addc_u32 s49, s49, 0
	s_waitcnt lgkmcnt(0)
	v_pk_mul_f32 v[84:85], v[84:85], v[100:101]
	v_pk_mul_f32 v[86:87], v[86:87], v[102:103]
	v_pk_mul_f32 v[80:81], v[80:81], v[96:97]
	v_pk_mul_f32 v[82:83], v[82:83], v[98:99]
	v_cvt_pk_bf16_f32 v90, v84, v85
	v_cvt_pk_bf16_f32 v91, v86, v87
	v_cvt_pk_bf16_f32 v88, v80, v81
	v_cvt_pk_bf16_f32 v89, v82, v83
	ds_read_b32 v80, v77 offset:64
	ds_read_b32 v81, v77 offset:324
	ds_read_b32 v82, v77 offset:584
	ds_read_b32 v83, v77 offset:844
	ds_read_b32 v84, v77 offset:1104
	ds_read_b32 v85, v77 offset:1364
	ds_read_b32 v86, v77 offset:1624
	ds_read_b32 v87, v77 offset:1884
	global_store_dwordx4 v104, v[88:91], s[48:49]
	s_add_u32 s48, s48, s50
	s_addc_u32 s49, s49, 0
	s_waitcnt lgkmcnt(0)
	v_pk_mul_f32 v[84:85], v[84:85], v[100:101]
	v_pk_mul_f32 v[86:87], v[86:87], v[102:103]
	v_pk_mul_f32 v[80:81], v[80:81], v[96:97]
	v_pk_mul_f32 v[82:83], v[82:83], v[98:99]
	v_cvt_pk_bf16_f32 v90, v84, v85
	v_cvt_pk_bf16_f32 v91, v86, v87
	v_cvt_pk_bf16_f32 v88, v80, v81
	v_cvt_pk_bf16_f32 v89, v82, v83
	ds_read_b32 v80, v77 offset:96
	ds_read_b32 v81, v77 offset:356
	ds_read_b32 v82, v77 offset:616
	ds_read_b32 v83, v77 offset:876
	ds_read_b32 v84, v77 offset:1136
	ds_read_b32 v85, v77 offset:1396
	ds_read_b32 v86, v77 offset:1656
	ds_read_b32 v87, v77 offset:1916
	global_store_dwordx4 v104, v[88:91], s[48:49]
	s_add_u32 s48, s48, s50
	s_addc_u32 s49, s49, 0
	s_waitcnt lgkmcnt(0)
	v_pk_mul_f32 v[84:85], v[84:85], v[100:101]
	v_pk_mul_f32 v[86:87], v[86:87], v[102:103]
	v_pk_mul_f32 v[80:81], v[80:81], v[96:97]
	v_pk_mul_f32 v[82:83], v[82:83], v[98:99]
	v_cvt_pk_bf16_f32 v90, v84, v85
	v_cvt_pk_bf16_f32 v91, v86, v87
	v_cvt_pk_bf16_f32 v88, v80, v81
	v_cvt_pk_bf16_f32 v89, v82, v83
	ds_read_b32 v80, v77 offset:128
	ds_read_b32 v81, v77 offset:388
	ds_read_b32 v82, v77 offset:648
	ds_read_b32 v83, v77 offset:908
	ds_read_b32 v84, v77 offset:1168
	ds_read_b32 v85, v77 offset:1428
	ds_read_b32 v86, v77 offset:1688
	ds_read_b32 v87, v77 offset:1948
	global_store_dwordx4 v104, v[88:91], s[48:49]
	s_add_u32 s48, s48, s50
	s_addc_u32 s49, s49, 0
	s_waitcnt lgkmcnt(0)
	v_pk_mul_f32 v[84:85], v[84:85], v[100:101]
	v_pk_mul_f32 v[86:87], v[86:87], v[102:103]
	v_pk_mul_f32 v[80:81], v[80:81], v[96:97]
	v_pk_mul_f32 v[82:83], v[82:83], v[98:99]
	v_cvt_pk_bf16_f32 v90, v84, v85
	v_cvt_pk_bf16_f32 v91, v86, v87
	v_cvt_pk_bf16_f32 v88, v80, v81
	v_cvt_pk_bf16_f32 v89, v82, v83
	ds_read_b32 v80, v77 offset:160
	ds_read_b32 v81, v77 offset:420
	ds_read_b32 v82, v77 offset:680
	ds_read_b32 v83, v77 offset:940
	ds_read_b32 v84, v77 offset:1200
	ds_read_b32 v85, v77 offset:1460
	ds_read_b32 v86, v77 offset:1720
	ds_read_b32 v87, v77 offset:1980
	global_store_dwordx4 v104, v[88:91], s[48:49]
	s_add_u32 s48, s48, s50
	s_addc_u32 s49, s49, 0
	s_waitcnt lgkmcnt(0)
	v_pk_mul_f32 v[84:85], v[84:85], v[100:101]
	v_pk_mul_f32 v[86:87], v[86:87], v[102:103]
	v_pk_mul_f32 v[80:81], v[80:81], v[96:97]
	v_pk_mul_f32 v[82:83], v[82:83], v[98:99]
	v_cvt_pk_bf16_f32 v90, v84, v85
	v_cvt_pk_bf16_f32 v91, v86, v87
	v_cvt_pk_bf16_f32 v88, v80, v81
	v_cvt_pk_bf16_f32 v89, v82, v83
	ds_read_b32 v80, v77 offset:192
	ds_read_b32 v81, v77 offset:452
	ds_read_b32 v82, v77 offset:712
	ds_read_b32 v83, v77 offset:972
	ds_read_b32 v84, v77 offset:1232
	ds_read_b32 v85, v77 offset:1492
	ds_read_b32 v86, v77 offset:1752
	ds_read_b32 v87, v77 offset:2012
	global_store_dwordx4 v104, v[88:91], s[48:49]
	s_add_u32 s48, s48, s50
	s_addc_u32 s49, s49, 0
	s_waitcnt lgkmcnt(0)
	v_pk_mul_f32 v[84:85], v[84:85], v[100:101]
	v_pk_mul_f32 v[86:87], v[86:87], v[102:103]
	v_pk_mul_f32 v[80:81], v[80:81], v[96:97]
	v_pk_mul_f32 v[82:83], v[82:83], v[98:99]
	v_cvt_pk_bf16_f32 v90, v84, v85
	v_cvt_pk_bf16_f32 v91, v86, v87
	v_cvt_pk_bf16_f32 v88, v80, v81
	v_cvt_pk_bf16_f32 v89, v82, v83
	ds_read_b32 v80, v77 offset:224
	ds_read_b32 v81, v77 offset:484
	ds_read_b32 v82, v77 offset:744
	ds_read_b32 v83, v77 offset:1004
	ds_read_b32 v84, v77 offset:1264
	ds_read_b32 v85, v77 offset:1524
	ds_read_b32 v86, v77 offset:1784
	ds_read_b32 v87, v77 offset:2044
	global_store_dwordx4 v104, v[88:91], s[48:49]
	s_add_u32 s48, s48, s50
	s_addc_u32 s49, s49, 0
	s_waitcnt lgkmcnt(0)
	v_pk_mul_f32 v[84:85], v[84:85], v[100:101]
	v_pk_mul_f32 v[86:87], v[86:87], v[102:103]
	v_pk_mul_f32 v[80:81], v[80:81], v[96:97]
	v_pk_mul_f32 v[82:83], v[82:83], v[98:99]
	v_cvt_pk_bf16_f32 v90, v84, v85
	v_cvt_pk_bf16_f32 v91, v86, v87
	v_cvt_pk_bf16_f32 v88, v80, v81
	v_cvt_pk_bf16_f32 v89, v82, v83
	global_store_dwordx4 v104, v[88:91], s[48:49]

; #define PG8_STAGE(bufoff, gbase, voff) do { _Pragma("unroll") for (int _i = 0; _i < 2; ++_i) \
;         __builtin_amdgcn_global_load_lds((const unsigned*)((const char*)(gbase) + (voff)[_i]), (LAS unsigned*)(lds + (bufoff) + ldsw + _i * 8192), 16, 0, 0); } while (0)
; #define PG8_LDA(dst, b, h) do { _Pragma("unroll") for (int m = 0; m < 4; ++m) _Pragma("unroll") for (int k = 0; k < 2; ++k) dst[m][k] = *(const LAS bf16x8*)(lds + PG8_SA(b, h) + aoff + m * 2048 + k * 1024); } while (0)
; #define PG8_LDB(dst, b, h) do { _Pragma("unroll") for (int n = 0; n < 2; ++n) _Pragma("unroll") for (int k = 0; k < 2; ++k) dst[n][k] = *(const LAS bf16x8*)(lds + PG8_SB(b, h) + boff + n * 2048 + k * 1024); } while (0)
; #define PG8_MMA(ai, bj, At, Bt) do { __builtin_amdgcn_s_setprio(1); _Pragma("unroll") for (int m = 0; m < 4; ++m) _Pragma("unroll") for (int n = 0; n < 2; ++n) _Pragma("unroll") for (int k = 0; k < 2; ++k) \
;         acc[ai][bj][m][n] = __builtin_amdgcn_mfma_f32_16x16x32_bf16(Bt[n][k], At[m][k], acc[ai][bj][m][n], 0, 0, 0); __builtin_amdgcn_s_setprio(0); } while (0)
; #define PG8_WAIT_V(n) asm volatile("s_waitcnt vmcnt(" #n ")" ::: "memory")
; #define PG8_WAIT_L(n) asm volatile("s_waitcnt lgkmcnt(" #n ")" ::: "memory")
; #define PG8_BAR __builtin_amdgcn_s_barrier()
; #define PG8_SCHED __builtin_amdgcn_sched_barrier(0)
; __device__ __forceinline__ void gemm_phase(LAS unsigned char* lds, const Gemm g, const StaticOrder& S, const Epi& E) {
;     ...
;         for (int t = 0; t < nt; t += 2) {
;             const bool last = (t == nt - 2);
;             const char* a1 = cA + (size_t)(t + 1) * kstep;
;             const char* a2 = last ? nA : cA + (size_t)(t + 2) * kstep; const char* b2 = last ? nB : cB + (size_t)(t + 2) * kstep;
;             const char* a3 = a2 + kstep; const char* b3 = b2 + kstep;
;             PG8_LDB(B0, 0, 0); PG8_LDB(B1, 0, 1); PG8_SCHED; PG8_LDA(At, 0, 0); PG8_STAGE(PG8_SA(1, 1), a1 + hstep, voffA);
;             PG8_WAIT_V(8); PG8_WAIT_L(0); PG8_BAR; PG8_MMA(0, 0, At, B0); PG8_MMA(0, 1, At, B1); PG8_BAR; PG8_SCHED;
;             PG8_LDA(At, 0, 1); PG8_STAGE(PG8_SB(0, 0), b2, voffB); PG8_STAGE(PG8_SB(0, 1), b2 + hstep, voffB); PG8_STAGE(PG8_SA(0, 0), a2, voffA);
;             PG8_WAIT_V(8); PG8_WAIT_L(0); PG8_BAR; PG8_MMA(1, 0, At, B0); PG8_MMA(1, 1, At, B1); PG8_BAR; PG8_SCHED;
.LBB0_662:
	s_add_i32 s42, s22, 2
	s_add_u32 s10, s40, 0x80
	s_addc_u32 s11, s41, 0
	s_add_i32 s43, 0, 0x10000
	s_cmp_eq_u32 s73, s22
	s_cselect_b32 s23, s19, s11
	s_cselect_b32 s22, s18, s10
	s_cselect_b32 s99, s21, s25
	s_cselect_b32 s98, s20, s24
	s_add_i32 s47, 0, 0x14000
	v_add_u32_e32 v142, s43, v215
	v_add_u32_e32 v158, s47, v215
	ds_read_b128 v[130:133], v142
	ds_read_b128 v[134:137], v142 offset:1024
	ds_read_b128 v[138:141], v142 offset:2048
	ds_read_b128 v[142:145], v142 offset:3072
	ds_read_b128 v[146:149], v158
	ds_read_b128 v[150:153], v158 offset:1024
	ds_read_b128 v[154:157], v158 offset:2048
	ds_read_b128 v[158:161], v158 offset:3072
	s_add_i32 m0, s77, 0xc000
	ds_read_b128 v[162:165], v221
	ds_read_b128 v[188:191], v221 offset:1024
	ds_read_b128 v[192:195], v221 offset:2048
	ds_read_b128 v[196:199], v221 offset:3072
	ds_read_b128 v[200:203], v221 offset:4096
	ds_read_b128 v[222:225], v221 offset:5120
	ds_read_b128 v[226:229], v221 offset:6144
	ds_read_b128 v[230:233], v221 offset:7168
	global_load_lds_dwordx4 v184, s[40:41]
	s_add_i32 m0, s77, 0xe000
	s_add_u32 s100, s98, s64
	s_addc_u32 s101, s99, 0
	global_load_lds_dwordx4 v186, s[40:41]
	s_waitcnt vmcnt(8)
	s_waitcnt lgkmcnt(0)
	s_barrier
	s_setprio 1
	s_waitcnt lgkmcnt(0)
	v_mfma_f32_16x16x32_bf16 v[126:129], v[130:133], v[162:165], v[126:129]
	v_mfma_f32_16x16x32_bf16 v[118:121], v[138:141], v[162:165], v[118:121]
	v_mfma_f32_16x16x32_bf16 v[110:113], v[130:133], v[192:195], v[110:113]
	v_mfma_f32_16x16x32_bf16 v[102:105], v[138:141], v[192:195], v[102:105]
	v_mfma_f32_16x16x32_bf16 v[94:97], v[130:133], v[200:203], v[94:97]
	v_mfma_f32_16x16x32_bf16 v[86:89], v[138:141], v[200:203], v[86:89]
	v_mfma_f32_16x16x32_bf16 v[78:81], v[130:133], v[226:229], v[78:81]
	v_mfma_f32_16x16x32_bf16 v[70:73], v[138:141], v[226:229], v[70:73]
	v_mfma_f32_16x16x32_bf16 v[126:129], v[134:137], v[188:191], v[126:129]
	v_mfma_f32_16x16x32_bf16 v[118:121], v[142:145], v[188:191], v[118:121]
	v_mfma_f32_16x16x32_bf16 v[110:113], v[134:137], v[196:199], v[110:113]
	v_mfma_f32_16x16x32_bf16 v[102:105], v[142:145], v[196:199], v[102:105]
	v_mfma_f32_16x16x32_bf16 v[94:97], v[134:137], v[222:225], v[94:97]
	v_mfma_f32_16x16x32_bf16 v[86:89], v[142:145], v[222:225], v[86:89]
	v_mfma_f32_16x16x32_bf16 v[78:81], v[134:137], v[230:233], v[78:81]
	v_mfma_f32_16x16x32_bf16 v[70:73], v[142:145], v[230:233], v[70:73]
	v_mfma_f32_16x16x32_bf16 v[122:125], v[146:149], v[162:165], v[122:125]
	v_mfma_f32_16x16x32_bf16 v[114:117], v[154:157], v[162:165], v[114:117]
	v_mfma_f32_16x16x32_bf16 v[106:109], v[146:149], v[192:195], v[106:109]
	v_mfma_f32_16x16x32_bf16 v[98:101], v[154:157], v[192:195], v[98:101]
	v_mfma_f32_16x16x32_bf16 v[90:93], v[146:149], v[200:203], v[90:93]
	v_mfma_f32_16x16x32_bf16 v[82:85], v[154:157], v[200:203], v[82:85]
	v_mfma_f32_16x16x32_bf16 v[74:77], v[146:149], v[226:229], v[74:77]
	v_mfma_f32_16x16x32_bf16 v[66:69], v[154:157], v[226:229], v[66:69]
	v_mfma_f32_16x16x32_bf16 v[122:125], v[150:153], v[188:191], v[122:125]
	v_mfma_f32_16x16x32_bf16 v[114:117], v[158:161], v[188:191], v[114:117]
	v_mfma_f32_16x16x32_bf16 v[106:109], v[150:153], v[196:199], v[106:109]
	v_mfma_f32_16x16x32_bf16 v[98:101], v[158:161], v[196:199], v[98:101]
	v_mfma_f32_16x16x32_bf16 v[90:93], v[150:153], v[222:225], v[90:93]
	v_mfma_f32_16x16x32_bf16 v[82:85], v[158:161], v[222:225], v[82:85]
	v_mfma_f32_16x16x32_bf16 v[74:77], v[150:153], v[230:233], v[74:77]
	v_mfma_f32_16x16x32_bf16 v[66:69], v[158:161], v[230:233], v[66:69]
	s_setprio 0
	s_barrier
	s_add_i32 s43, s43, s76
	s_mov_b32 m0, s43
	ds_read_b128 v[162:165], v221 offset:16384
	ds_read_b128 v[188:191], v221 offset:17408
	ds_read_b128 v[192:195], v221 offset:18432
	ds_read_b128 v[196:199], v221 offset:19456
	ds_read_b128 v[200:203], v221 offset:20480
	ds_read_b128 v[222:225], v221 offset:21504
	ds_read_b128 v[226:229], v221 offset:22528
	ds_read_b128 v[230:233], v221 offset:23552
	global_load_lds_dwordx4 v0, s[98:99]
	s_add_i32 m0, s43, 0x2000
	s_add_i32 s43, s47, s76
	global_load_lds_dwordx4 v180, s[98:99]
	s_mov_b32 m0, s43
	s_nop 0
	global_load_lds_dwordx4 v0, s[100:101]
	s_add_i32 m0, s43, 0x2000
	s_nop 0
	global_load_lds_dwordx4 v180, s[100:101]
	s_mov_b32 m0, s77
	s_nop 0
	global_load_lds_dwordx4 v176, s[22:23]
	s_mov_b32 m0, s88
	s_nop 0
	global_load_lds_dwordx4 v178, s[22:23]
	s_waitcnt vmcnt(8)
	s_waitcnt lgkmcnt(0)
	s_barrier
	s_setprio 1
	s_waitcnt lgkmcnt(0)
	v_mfma_f32_16x16x32_bf16 v[62:65], v[130:133], v[162:165], v[62:65]
	v_mfma_f32_16x16x32_bf16 v[54:57], v[138:141], v[162:165], v[54:57]
	v_mfma_f32_16x16x32_bf16 v[46:49], v[130:133], v[192:195], v[46:49]
	v_mfma_f32_16x16x32_bf16 v[38:41], v[138:141], v[192:195], v[38:41]
	v_mfma_f32_16x16x32_bf16 v[30:33], v[130:133], v[200:203], v[30:33]
	v_mfma_f32_16x16x32_bf16 v[22:25], v[138:141], v[200:203], v[22:25]
	v_mfma_f32_16x16x32_bf16 v[14:17], v[130:133], v[226:229], v[14:17]
	v_mfma_f32_16x16x32_bf16 v[6:9], v[138:141], v[226:229], v[6:9]
	v_mfma_f32_16x16x32_bf16 v[62:65], v[134:137], v[188:191], v[62:65]
	v_mfma_f32_16x16x32_bf16 v[54:57], v[142:145], v[188:191], v[54:57]
	v_mfma_f32_16x16x32_bf16 v[46:49], v[134:137], v[196:199], v[46:49]
	v_mfma_f32_16x16x32_bf16 v[38:41], v[142:145], v[196:199], v[38:41]
	v_mfma_f32_16x16x32_bf16 v[30:33], v[134:137], v[222:225], v[30:33]
	v_mfma_f32_16x16x32_bf16 v[22:25], v[142:145], v[222:225], v[22:25]
	v_mfma_f32_16x16x32_bf16 v[14:17], v[134:137], v[230:233], v[14:17]
	v_mfma_f32_16x16x32_bf16 v[6:9], v[142:145], v[230:233], v[6:9]
	v_mfma_f32_16x16x32_bf16 v[58:61], v[146:149], v[162:165], v[58:61]
	v_mfma_f32_16x16x32_bf16 v[50:53], v[154:157], v[162:165], v[50:53]
	v_mfma_f32_16x16x32_bf16 v[42:45], v[146:149], v[192:195], v[42:45]
	v_mfma_f32_16x16x32_bf16 v[34:37], v[154:157], v[192:195], v[34:37]
	v_mfma_f32_16x16x32_bf16 v[26:29], v[146:149], v[200:203], v[26:29]
	v_mfma_f32_16x16x32_bf16 v[18:21], v[154:157], v[200:203], v[18:21]
	v_mfma_f32_16x16x32_bf16 v[10:13], v[146:149], v[226:229], v[10:13]
	v_mfma_f32_16x16x32_bf16 v[2:5], v[154:157], v[226:229], v[2:5]
	v_mfma_f32_16x16x32_bf16 v[58:61], v[150:153], v[188:191], v[58:61]
	v_mfma_f32_16x16x32_bf16 v[50:53], v[158:161], v[188:191], v[50:53]
	v_mfma_f32_16x16x32_bf16 v[42:45], v[150:153], v[196:199], v[42:45]
	v_mfma_f32_16x16x32_bf16 v[34:37], v[158:161], v[196:199], v[34:37]
	v_mfma_f32_16x16x32_bf16 v[26:29], v[150:153], v[222:225], v[26:29]
	v_mfma_f32_16x16x32_bf16 v[18:21], v[158:161], v[222:225], v[18:21]
	v_mfma_f32_16x16x32_bf16 v[10:13], v[150:153], v[230:233], v[10:13]
	v_mfma_f32_16x16x32_bf16 v[2:5], v[158:161], v[230:233], v[2:5]
	s_setprio 0
	s_barrier
; #define PG8_STAGE(bufoff, gbase, voff) do { _Pragma("unroll") for (int _i = 0; _i < 2; ++_i) \
;         __builtin_amdgcn_global_load_lds((const unsigned*)((const char*)(gbase) + (voff)[_i]), (LAS unsigned*)(lds + (bufoff) + ldsw + _i * 8192), 16, 0, 0); } while (0)
; #define PG8_LDA(dst, b, h) do { _Pragma("unroll") for (int m = 0; m < 4; ++m) _Pragma("unroll") for (int k = 0; k < 2; ++k) dst[m][k] = *(const LAS bf16x8*)(lds + PG8_SA(b, h) + aoff + m * 2048 + k * 1024); } while (0)
; #define PG8_LDB(dst, b, h) do { _Pragma("unroll") for (int n = 0; n < 2; ++n) _Pragma("unroll") for (int k = 0; k < 2; ++k) dst[n][k] = *(const LAS bf16x8*)(lds + PG8_SB(b, h) + boff + n * 2048 + k * 1024); } while (0)
; #define PG8_MMA(ai, bj, At, Bt) do { __builtin_amdgcn_s_setprio(1); _Pragma("unroll") for (int m = 0; m < 4; ++m) _Pragma("unroll") for (int n = 0; n < 2; ++n) _Pragma("unroll") for (int k = 0; k < 2; ++k) \
;         acc[ai][bj][m][n] = __builtin_amdgcn_mfma_f32_16x16x32_bf16(Bt[n][k], At[m][k], acc[ai][bj][m][n], 0, 0, 0); __builtin_amdgcn_s_setprio(0); } while (0)
; #define PG8_WAIT_V(n) asm volatile("s_waitcnt vmcnt(" #n ")" ::: "memory")
; #define PG8_WAIT_L(n) asm volatile("s_waitcnt lgkmcnt(" #n ")" ::: "memory")
; #define PG8_BAR __builtin_amdgcn_s_barrier()
; #define PG8_SCHED __builtin_amdgcn_sched_barrier(0)
; __device__ __forceinline__ void gemm_phase(LAS unsigned char* lds, const Gemm g, const StaticOrder& S, const Epi& E) {
;     ...
;             PG8_LDB(B0, 1, 0); PG8_LDB(B1, 1, 1); PG8_SCHED; PG8_LDA(At, 1, 0); PG8_STAGE(PG8_SA(0, 1), a2 + hstep, voffA);
;             PG8_WAIT_V(8); PG8_WAIT_L(0); PG8_BAR; PG8_MMA(0, 0, At, B0); PG8_MMA(0, 1, At, B1); PG8_BAR; PG8_SCHED;
;             PG8_LDA(At, 1, 1); PG8_STAGE(PG8_SB(1, 0), b3, voffB); PG8_STAGE(PG8_SB(1, 1), b3 + hstep, voffB); PG8_STAGE(PG8_SA(1, 0), a3, voffA);
;             PG8_WAIT_V(8); PG8_WAIT_L(0); PG8_BAR; PG8_MMA(1, 0, At, B0); PG8_MMA(1, 1, At, B1); PG8_BAR; PG8_SCHED;
;         }
;         if (wr == 0) PG8_BAR;
	s_add_i32 s43, 0, 0x1c000
	v_add_u32_e32 v142, s89, v215
	v_add_u32_e32 v158, s43, v215
	ds_read_b128 v[130:133], v142
	ds_read_b128 v[134:137], v142 offset:1024
	ds_read_b128 v[138:141], v142 offset:2048
	ds_read_b128 v[142:145], v142 offset:3072
	ds_read_b128 v[146:149], v158
	ds_read_b128 v[150:153], v158 offset:1024
	ds_read_b128 v[154:157], v158 offset:2048
	ds_read_b128 v[158:161], v158 offset:3072
	s_add_u32 s10, s22, s64
	s_addc_u32 s11, s23, 0
	s_mov_b32 m0, s26
	ds_read_b128 v[162:165], v221 offset:32768
	ds_read_b128 v[188:191], v221 offset:33792
	ds_read_b128 v[192:195], v221 offset:34816
	ds_read_b128 v[196:199], v221 offset:35840
	ds_read_b128 v[200:203], v221 offset:36864
	ds_read_b128 v[222:225], v221 offset:37888
	ds_read_b128 v[226:229], v221 offset:38912
	ds_read_b128 v[230:233], v221 offset:39936
	global_load_lds_dwordx4 v176, s[10:11]
	s_mov_b32 m0, s48
	s_nop 0
	global_load_lds_dwordx4 v178, s[10:11]
	s_waitcnt vmcnt(8)
	s_waitcnt lgkmcnt(0)
	s_barrier
	s_setprio 1
	s_waitcnt lgkmcnt(0)
	v_mfma_f32_16x16x32_bf16 v[126:129], v[130:133], v[162:165], v[126:129]
	v_mfma_f32_16x16x32_bf16 v[118:121], v[138:141], v[162:165], v[118:121]
	v_mfma_f32_16x16x32_bf16 v[110:113], v[130:133], v[192:195], v[110:113]
	v_mfma_f32_16x16x32_bf16 v[102:105], v[138:141], v[192:195], v[102:105]
	v_mfma_f32_16x16x32_bf16 v[94:97], v[130:133], v[200:203], v[94:97]
	v_mfma_f32_16x16x32_bf16 v[86:89], v[138:141], v[200:203], v[86:89]
	v_mfma_f32_16x16x32_bf16 v[78:81], v[130:133], v[226:229], v[78:81]
	v_mfma_f32_16x16x32_bf16 v[70:73], v[138:141], v[226:229], v[70:73]
	v_mfma_f32_16x16x32_bf16 v[126:129], v[134:137], v[188:191], v[126:129]
	v_mfma_f32_16x16x32_bf16 v[118:121], v[142:145], v[188:191], v[118:121]
	v_mfma_f32_16x16x32_bf16 v[110:113], v[134:137], v[196:199], v[110:113]
	v_mfma_f32_16x16x32_bf16 v[102:105], v[142:145], v[196:199], v[102:105]
	v_mfma_f32_16x16x32_bf16 v[94:97], v[134:137], v[222:225], v[94:97]
	v_mfma_f32_16x16x32_bf16 v[86:89], v[142:145], v[222:225], v[86:89]
	v_mfma_f32_16x16x32_bf16 v[78:81], v[134:137], v[230:233], v[78:81]
	v_mfma_f32_16x16x32_bf16 v[70:73], v[142:145], v[230:233], v[70:73]
	v_mfma_f32_16x16x32_bf16 v[122:125], v[146:149], v[162:165], v[122:125]
	v_mfma_f32_16x16x32_bf16 v[114:117], v[154:157], v[162:165], v[114:117]
	v_mfma_f32_16x16x32_bf16 v[106:109], v[146:149], v[192:195], v[106:109]
	v_mfma_f32_16x16x32_bf16 v[98:101], v[154:157], v[192:195], v[98:101]
	v_mfma_f32_16x16x32_bf16 v[90:93], v[146:149], v[200:203], v[90:93]
	v_mfma_f32_16x16x32_bf16 v[82:85], v[154:157], v[200:203], v[82:85]
	v_mfma_f32_16x16x32_bf16 v[74:77], v[146:149], v[226:229], v[74:77]
	v_mfma_f32_16x16x32_bf16 v[66:69], v[154:157], v[226:229], v[66:69]
	v_mfma_f32_16x16x32_bf16 v[122:125], v[150:153], v[188:191], v[122:125]
	v_mfma_f32_16x16x32_bf16 v[114:117], v[158:161], v[188:191], v[114:117]
	v_mfma_f32_16x16x32_bf16 v[106:109], v[150:153], v[196:199], v[106:109]
	v_mfma_f32_16x16x32_bf16 v[98:101], v[158:161], v[196:199], v[98:101]
	v_mfma_f32_16x16x32_bf16 v[90:93], v[150:153], v[222:225], v[90:93]
	v_mfma_f32_16x16x32_bf16 v[82:85], v[158:161], v[222:225], v[82:85]
	v_mfma_f32_16x16x32_bf16 v[74:77], v[150:153], v[230:233], v[74:77]
	v_mfma_f32_16x16x32_bf16 v[66:69], v[158:161], v[230:233], v[66:69]
	s_setprio 0
	s_barrier
	s_add_i32 m0, s89, s76
	s_add_u32 s10, s98, 0x80
	s_addc_u32 s11, s99, 0
	ds_read_b128 v[162:165], v221 offset:49152
	ds_read_b128 v[188:191], v221 offset:50176
	ds_read_b128 v[192:195], v221 offset:51200
	ds_read_b128 v[196:199], v221 offset:52224
	ds_read_b128 v[200:203], v221 offset:53248
	ds_read_b128 v[222:225], v221 offset:54272
	ds_read_b128 v[226:229], v221 offset:55296
	ds_read_b128 v[230:233], v221 offset:56320
	global_load_lds_dwordx4 v0, s[10:11]
	s_add_i32 m0, m0, 0x2000
	s_nop 0
	global_load_lds_dwordx4 v180, s[10:11]
	s_add_i32 m0, s43, s76
	s_add_u32 s10, s100, 0x80
	s_addc_u32 s11, s101, 0
	global_load_lds_dwordx4 v0, s[10:11]
	s_add_i32 m0, m0, 0x2000
	s_nop 0
	global_load_lds_dwordx4 v180, s[10:11]
	s_mov_b32 m0, s49
	s_add_u32 s10, s22, 0x80
	s_addc_u32 s11, s23, 0
	global_load_lds_dwordx4 v176, s[10:11]
	s_mov_b32 m0, s72
	s_nop 0
	global_load_lds_dwordx4 v178, s[10:11]
	s_waitcnt vmcnt(8)
	s_waitcnt lgkmcnt(0)
	s_barrier
	s_setprio 1
	s_waitcnt lgkmcnt(0)
	v_mfma_f32_16x16x32_bf16 v[62:65], v[130:133], v[162:165], v[62:65]
	v_mfma_f32_16x16x32_bf16 v[54:57], v[138:141], v[162:165], v[54:57]
	v_mfma_f32_16x16x32_bf16 v[46:49], v[130:133], v[192:195], v[46:49]
	v_mfma_f32_16x16x32_bf16 v[38:41], v[138:141], v[192:195], v[38:41]
	v_mfma_f32_16x16x32_bf16 v[30:33], v[130:133], v[200:203], v[30:33]
	v_mfma_f32_16x16x32_bf16 v[22:25], v[138:141], v[200:203], v[22:25]
	v_mfma_f32_16x16x32_bf16 v[14:17], v[130:133], v[226:229], v[14:17]
	v_mfma_f32_16x16x32_bf16 v[6:9], v[138:141], v[226:229], v[6:9]
	v_mfma_f32_16x16x32_bf16 v[62:65], v[134:137], v[188:191], v[62:65]
	v_mfma_f32_16x16x32_bf16 v[54:57], v[142:145], v[188:191], v[54:57]
	v_mfma_f32_16x16x32_bf16 v[46:49], v[134:137], v[196:199], v[46:49]
	v_mfma_f32_16x16x32_bf16 v[38:41], v[142:145], v[196:199], v[38:41]
	v_mfma_f32_16x16x32_bf16 v[30:33], v[134:137], v[222:225], v[30:33]
	v_mfma_f32_16x16x32_bf16 v[22:25], v[142:145], v[222:225], v[22:25]
	v_mfma_f32_16x16x32_bf16 v[14:17], v[134:137], v[230:233], v[14:17]
	v_mfma_f32_16x16x32_bf16 v[6:9], v[142:145], v[230:233], v[6:9]
	v_mfma_f32_16x16x32_bf16 v[58:61], v[146:149], v[162:165], v[58:61]
	v_mfma_f32_16x16x32_bf16 v[50:53], v[154:157], v[162:165], v[50:53]
	v_mfma_f32_16x16x32_bf16 v[42:45], v[146:149], v[192:195], v[42:45]
	v_mfma_f32_16x16x32_bf16 v[34:37], v[154:157], v[192:195], v[34:37]
	v_mfma_f32_16x16x32_bf16 v[26:29], v[146:149], v[200:203], v[26:29]
	v_mfma_f32_16x16x32_bf16 v[18:21], v[154:157], v[200:203], v[18:21]
	v_mfma_f32_16x16x32_bf16 v[10:13], v[146:149], v[226:229], v[10:13]
	v_mfma_f32_16x16x32_bf16 v[2:5], v[154:157], v[226:229], v[2:5]
	v_mfma_f32_16x16x32_bf16 v[58:61], v[150:153], v[188:191], v[58:61]
	v_mfma_f32_16x16x32_bf16 v[50:53], v[158:161], v[188:191], v[50:53]
	v_mfma_f32_16x16x32_bf16 v[42:45], v[150:153], v[196:199], v[42:45]
	v_mfma_f32_16x16x32_bf16 v[34:37], v[158:161], v[196:199], v[34:37]
	v_mfma_f32_16x16x32_bf16 v[26:29], v[150:153], v[222:225], v[26:29]
	v_mfma_f32_16x16x32_bf16 v[18:21], v[158:161], v[222:225], v[18:21]
	v_mfma_f32_16x16x32_bf16 v[10:13], v[150:153], v[230:233], v[10:13]
	v_mfma_f32_16x16x32_bf16 v[2:5], v[158:161], v[230:233], v[2:5]
	s_setprio 0
	s_barrier
	s_add_u32 s40, s40, 0x100
	s_addc_u32 s41, s41, 0
	s_add_u32 s24, s24, 0x100
	s_addc_u32 s25, s25, 0
	s_cmp_ge_u32 s42, s68
	s_mov_b32 s22, s42
	s_cbranch_scc0 .LBB0_662
	s_and_b64 vcc, exec, s[14:15]
	s_cbranch_vccz .LBB0_665
	s_barrier
